# same as v33 but the static priority raise goes to waves 0-3 instead of 4-7
# baseline (speedup 1.0000x reference)
; template <class Epi, bool ALIGN_EPI>
; __device__ __forceinline__ void gemm_phase(LAS unsigned char* lds, const Gemm g, const StaticOrder S, const Epi E) {
;     ...
;         const bool has_next = S.next(ui + 1, nxt);
;         const char* nA = has_next ? (const char*)g.A + (size_t)nxt.pm * tstepA + PG8_KOFS(nxt) : cA; const char* nB = has_next ? (const char*)g.Bt + (size_t)nxt.pn * tstepB + PG8_KOFS(nxt) : cB;
;     ...
;         for (int a = 0; a < 2; ++a)
; #pragma unroll
;             for (int b = 0; b < 2; ++b)
; #pragma unroll
;                 for (int m = 0; m < 4; ++m)
; #pragma unroll
;                     for (int n = 0; n < 2; ++n) acc[a][b][m][n] = (f32x4){0.f, 0.f, 0.f, 0.f};
.LBB0_603:
	s_ashr_i32 s67, s66, 31
	s_lshl_b64 s[0:1], s[66:67], 19
	s_add_u32 s68, s94, s0
	s_addc_u32 s69, s95, s1
	s_and_b64 s[0:1], s[42:43], exec
	s_cselect_b32 s34, s69, s49
	s_cselect_b32 s35, s68, s48
	s_ashr_i32 s65, s64, 31
	s_lshl_b64 s[0:1], s[64:65], 19
	s_add_u32 s70, s58, s0
	s_addc_u32 s71, s72, s1
	s_and_b64 s[0:1], s[42:43], exec
	s_cselect_b32 s50, s71, s47
	s_cselect_b32 s51, s70, s46
	s_add_u32 s40, s48, 0x40080
	s_addc_u32 s41, s49, 0
	s_add_u32 s52, s46, 0x100
	v_mov_b32_e32 v0, 0
	s_addc_u32 s53, s47, 0
	s_mov_b32 s54, -2
	v_mov_b32_e32 v1, 0
	v_mov_b64_e32 v[2:3], 0
	v_mov_b64_e32 v[4:5], 0
	v_mov_b64_e32 v[6:7], 0
	v_mov_b64_e32 v[8:9], 0
	v_mov_b64_e32 v[10:11], 0
	v_mov_b64_e32 v[12:13], 0
	v_mov_b64_e32 v[14:15], 0
	v_mov_b64_e32 v[16:17], 0
	v_mov_b64_e32 v[18:19], 0
	v_mov_b64_e32 v[20:21], 0
	v_mov_b64_e32 v[22:23], 0
	v_mov_b64_e32 v[24:25], 0
	v_mov_b64_e32 v[26:27], 0
	v_mov_b64_e32 v[28:29], 0
	v_mov_b64_e32 v[30:31], 0
	v_mov_b64_e32 v[32:33], 0
	v_mov_b64_e32 v[34:35], 0
	v_mov_b64_e32 v[36:37], 0
	v_mov_b64_e32 v[38:39], 0
	v_mov_b64_e32 v[40:41], 0
	v_mov_b64_e32 v[42:43], 0
	v_mov_b64_e32 v[44:45], 0
	v_mov_b64_e32 v[46:47], 0
	v_mov_b64_e32 v[48:49], 0
	v_mov_b64_e32 v[50:51], 0
	v_mov_b64_e32 v[52:53], 0
	v_mov_b64_e32 v[54:55], 0
	v_mov_b64_e32 v[56:57], 0
	v_mov_b64_e32 v[58:59], 0
	v_mov_b64_e32 v[60:61], 0
	v_mov_b64_e32 v[62:63], 0
	v_mov_b64_e32 v[64:65], 0
	v_mov_b64_e32 v[66:67], 0
	v_mov_b64_e32 v[68:69], 0
	v_mov_b64_e32 v[70:71], 0
	v_mov_b64_e32 v[72:73], 0
	v_mov_b64_e32 v[74:75], 0
	v_mov_b64_e32 v[76:77], 0
	v_mov_b64_e32 v[78:79], 0
	v_mov_b64_e32 v[82:83], 0
	v_mov_b64_e32 v[84:85], 0
	v_mov_b64_e32 v[86:87], 0
	v_mov_b64_e32 v[88:89], 0
	v_mov_b64_e32 v[90:91], 0
	v_mov_b64_e32 v[92:93], 0
	v_mov_b64_e32 v[94:95], 0
	v_mov_b64_e32 v[96:97], 0
	v_mov_b64_e32 v[98:99], 0
	v_mov_b64_e32 v[100:101], 0
	v_mov_b64_e32 v[102:103], 0
	v_mov_b64_e32 v[104:105], 0
	v_mov_b64_e32 v[106:107], 0
	v_mov_b64_e32 v[108:109], 0
	v_mov_b64_e32 v[110:111], 0
	v_mov_b64_e32 v[112:113], 0
	v_mov_b64_e32 v[114:115], 0
	v_mov_b64_e32 v[116:117], 0
	v_mov_b64_e32 v[118:119], 0
	v_mov_b64_e32 v[120:121], 0
	v_mov_b64_e32 v[122:123], 0
	v_mov_b64_e32 v[124:125], 0
	v_mov_b64_e32 v[126:127], 0
	v_mov_b64_e32 v[128:129], 0
	v_readfirstlane_b32 s0, v167
	s_nop 3
	s_cmpk_gt_u32 s0, 0xff
	s_cbranch_scc1 .Lprio_k0
	s_setprio 1

; template <class Epi, bool ALIGN_EPI>
; __device__ __forceinline__ void gemm_phase(LAS unsigned char* lds, const Gemm g, const StaticOrder S, const Epi E) {
;     ...
;         for (int t = 0; t < nt; t += 2) {
;     ...
;         for (int a = 0; a < 2; ++a)
; #pragma unroll
;             for (int b = 0; b < 2; ++b)
; #pragma unroll
;                 for (int m = 0; m < 4; ++m)
; #pragma unroll
;                     for (int n = 0; n < 2; ++n) acc[a][b][m][n] = (f32x4){0.f, 0.f, 0.f, 0.f};
.LBB0_727:
	s_add_u32 s28, s50, 0x100
	v_mov_b32_e32 v0, 0
	s_addc_u32 s29, s51, 0
	s_mov_b32 s30, -2
	v_mov_b32_e32 v1, 0
	v_mov_b64_e32 v[2:3], 0
	v_mov_b64_e32 v[4:5], 0
	v_mov_b64_e32 v[6:7], 0
	v_mov_b64_e32 v[8:9], 0
	v_mov_b64_e32 v[10:11], 0
	v_mov_b64_e32 v[12:13], 0
	v_mov_b64_e32 v[14:15], 0
	v_mov_b64_e32 v[16:17], 0
	v_mov_b64_e32 v[18:19], 0
	v_mov_b64_e32 v[20:21], 0
	v_mov_b64_e32 v[22:23], 0
	v_mov_b64_e32 v[24:25], 0
	v_mov_b64_e32 v[26:27], 0
	v_mov_b64_e32 v[28:29], 0
	v_mov_b64_e32 v[30:31], 0
	v_mov_b64_e32 v[32:33], 0
	v_mov_b64_e32 v[34:35], 0
	v_mov_b64_e32 v[36:37], 0
	v_mov_b64_e32 v[38:39], 0
	v_mov_b64_e32 v[40:41], 0
	v_mov_b64_e32 v[42:43], 0
	v_mov_b64_e32 v[44:45], 0
	v_mov_b64_e32 v[46:47], 0
	v_mov_b64_e32 v[48:49], 0
	v_mov_b64_e32 v[50:51], 0
	v_mov_b64_e32 v[52:53], 0
	v_mov_b64_e32 v[54:55], 0
	v_mov_b64_e32 v[56:57], 0
	v_mov_b64_e32 v[58:59], 0
	v_mov_b64_e32 v[60:61], 0
	v_mov_b64_e32 v[62:63], 0
	v_mov_b64_e32 v[64:65], 0
	v_mov_b64_e32 v[66:67], 0
	v_mov_b64_e32 v[68:69], 0
	v_mov_b64_e32 v[70:71], 0
	v_mov_b64_e32 v[72:73], 0
	v_mov_b64_e32 v[74:75], 0
	v_mov_b64_e32 v[76:77], 0
	v_mov_b64_e32 v[78:79], 0
	v_mov_b64_e32 v[82:83], 0
	v_mov_b64_e32 v[84:85], 0
	v_mov_b64_e32 v[86:87], 0
	v_mov_b64_e32 v[88:89], 0
	v_mov_b64_e32 v[90:91], 0
	v_mov_b64_e32 v[92:93], 0
	v_mov_b64_e32 v[94:95], 0
	v_mov_b64_e32 v[96:97], 0
	v_mov_b64_e32 v[98:99], 0
	v_mov_b64_e32 v[100:101], 0
	v_mov_b64_e32 v[102:103], 0
	v_mov_b64_e32 v[104:105], 0
	v_mov_b64_e32 v[106:107], 0
	v_mov_b64_e32 v[108:109], 0
	v_mov_b64_e32 v[110:111], 0
	v_mov_b64_e32 v[112:113], 0
	v_mov_b64_e32 v[114:115], 0
	v_mov_b64_e32 v[116:117], 0
	v_mov_b64_e32 v[118:119], 0
	v_mov_b64_e32 v[120:121], 0
	v_mov_b64_e32 v[122:123], 0
	v_mov_b64_e32 v[124:125], 0
	v_mov_b64_e32 v[126:127], 0
	v_mov_b64_e32 v[128:129], 0
	v_readfirstlane_b32 s0, v167
	s_nop 3
	s_cmpk_gt_u32 s0, 0xff
	s_cbranch_scc1 .Lprio_k1
	s_setprio 1

; template <class Epi, bool ALIGN_EPI>
; __device__ __forceinline__ void gemm_phase(LAS unsigned char* lds, const Gemm g, const StaticOrder S, const Epi E) {
;     ...
;         const bool has_next = S.next(ui + 1, nxt);
;         const char* nA = has_next ? (const char*)g.A + (size_t)nxt.pm * tstepA + PG8_KOFS(nxt) : cA; const char* nB = has_next ? (const char*)g.Bt + (size_t)nxt.pn * tstepB + PG8_KOFS(nxt) : cB;
;     ...
;         for (int a = 0; a < 2; ++a)
; #pragma unroll
;             for (int b = 0; b < 2; ++b)
; #pragma unroll
;                 for (int m = 0; m < 4; ++m)
; #pragma unroll
;                     for (int n = 0; n < 2; ++n) acc[a][b][m][n] = (f32x4){0.f, 0.f, 0.f, 0.f};
.LBB0_852:
	s_ashr_i32 s53, s52, 31
	s_lshl_b64 s[0:1], s[52:53], 19
	s_add_u32 s62, s94, s0
	s_addc_u32 s63, s95, s1
	s_and_b64 s[0:1], s[42:43], exec
	s_cselect_b32 s34, s63, s67
	s_cselect_b32 s35, s62, s66
	s_ashr_i32 s51, s50, 31
	s_lshl_b64 s[0:1], s[50:51], 19
	v_readlane_b32 s2, v255, 14
	s_add_u32 s64, s2, s0
	v_readlane_b32 s0, v255, 15
	s_addc_u32 s65, s0, s1
	s_and_b64 s[0:1], s[42:43], exec
	s_cselect_b32 s51, s65, s45
	s_cselect_b32 s53, s64, s44
	s_add_u32 s2, s66, 0x40080
	s_addc_u32 s3, s67, 0
	s_add_u32 s58, s44, 0x100
	v_mov_b32_e32 v0, 0
	s_addc_u32 s61, s45, 0
	s_mov_b32 s68, -2
	v_mov_b32_e32 v1, 0
	v_mov_b64_e32 v[2:3], 0
	v_mov_b64_e32 v[4:5], 0
	v_mov_b64_e32 v[6:7], 0
	v_mov_b64_e32 v[8:9], 0
	v_mov_b64_e32 v[10:11], 0
	v_mov_b64_e32 v[12:13], 0
	v_mov_b64_e32 v[14:15], 0
	v_mov_b64_e32 v[16:17], 0
	v_mov_b64_e32 v[18:19], 0
	v_mov_b64_e32 v[20:21], 0
	v_mov_b64_e32 v[22:23], 0
	v_mov_b64_e32 v[24:25], 0
	v_mov_b64_e32 v[26:27], 0
	v_mov_b64_e32 v[28:29], 0
	v_mov_b64_e32 v[30:31], 0
	v_mov_b64_e32 v[32:33], 0
	v_mov_b64_e32 v[34:35], 0
	v_mov_b64_e32 v[36:37], 0
	v_mov_b64_e32 v[38:39], 0
	v_mov_b64_e32 v[40:41], 0
	v_mov_b64_e32 v[42:43], 0
	v_mov_b64_e32 v[44:45], 0
	v_mov_b64_e32 v[46:47], 0
	v_mov_b64_e32 v[48:49], 0
	v_mov_b64_e32 v[50:51], 0
	v_mov_b64_e32 v[52:53], 0
	v_mov_b64_e32 v[54:55], 0
	v_mov_b64_e32 v[56:57], 0
	v_mov_b64_e32 v[58:59], 0
	v_mov_b64_e32 v[60:61], 0
	v_mov_b64_e32 v[62:63], 0
	v_mov_b64_e32 v[64:65], 0
	v_mov_b64_e32 v[66:67], 0
	v_mov_b64_e32 v[68:69], 0
	v_mov_b64_e32 v[70:71], 0
	v_mov_b64_e32 v[72:73], 0
	v_mov_b64_e32 v[74:75], 0
	v_mov_b64_e32 v[76:77], 0
	v_mov_b64_e32 v[78:79], 0
	v_mov_b64_e32 v[82:83], 0
	v_mov_b64_e32 v[84:85], 0
	v_mov_b64_e32 v[86:87], 0
	v_mov_b64_e32 v[88:89], 0
	v_mov_b64_e32 v[90:91], 0
	v_mov_b64_e32 v[92:93], 0
	v_mov_b64_e32 v[94:95], 0
	v_mov_b64_e32 v[96:97], 0
	v_mov_b64_e32 v[98:99], 0
	v_mov_b64_e32 v[100:101], 0
	v_mov_b64_e32 v[102:103], 0
	v_mov_b64_e32 v[104:105], 0
	v_mov_b64_e32 v[106:107], 0
	v_mov_b64_e32 v[108:109], 0
	v_mov_b64_e32 v[110:111], 0
	v_mov_b64_e32 v[112:113], 0
	v_mov_b64_e32 v[114:115], 0
	v_mov_b64_e32 v[116:117], 0
	v_mov_b64_e32 v[118:119], 0
	v_mov_b64_e32 v[120:121], 0
	v_mov_b64_e32 v[122:123], 0
	v_mov_b64_e32 v[124:125], 0
	v_mov_b64_e32 v[126:127], 0
	v_mov_b64_e32 v[128:129], 0
	v_readfirstlane_b32 s0, v167
	s_nop 3
	s_cmpk_gt_u32 s0, 0xff
	s_cbranch_scc1 .Lprio_k2
	s_setprio 1

; template <class Epi, bool ALIGN_EPI>
; __device__ __forceinline__ void gemm_phase(LAS unsigned char* lds, const Gemm g, const StaticOrder S, const Epi E) {
;     ...
;         const bool has_next = S.next(ui + 1, nxt);
;         const char* nA = has_next ? (const char*)g.A + (size_t)nxt.pm * tstepA + PG8_KOFS(nxt) : cA; const char* nB = has_next ? (const char*)g.Bt + (size_t)nxt.pn * tstepB + PG8_KOFS(nxt) : cB;
;     ...
;         for (int a = 0; a < 2; ++a)
; #pragma unroll
;             for (int b = 0; b < 2; ++b)
; #pragma unroll
;                 for (int m = 0; m < 4; ++m)
; #pragma unroll
;                     for (int n = 0; n < 2; ++n) acc[a][b][m][n] = (f32x4){0.f, 0.f, 0.f, 0.f};
.LBB0_1430:
	s_ashr_i32 s49, s48, 31
	s_lshl_b64 s[0:1], s[48:49], 19
	v_readlane_b32 s12, v255, 29
	s_add_u32 s52, s12, s0
	v_readlane_b32 s0, v255, 30
	s_addc_u32 s53, s0, s1
	s_and_b64 s[0:1], s[44:45], exec
	s_cselect_b32 s34, s53, s65
	s_cselect_b32 s35, s52, s64
	s_add_u32 s49, s64, 0x100
	v_mov_b32_e32 v0, 0
	s_addc_u32 s55, s65, 0
	s_mov_b32 s71, -2
	v_mov_b32_e32 v1, 0
	v_mov_b64_e32 v[2:3], 0
	v_mov_b64_e32 v[4:5], 0
	v_mov_b64_e32 v[6:7], 0
	v_mov_b64_e32 v[8:9], 0
	v_mov_b64_e32 v[10:11], 0
	v_mov_b64_e32 v[12:13], 0
	v_mov_b64_e32 v[14:15], 0
	v_mov_b64_e32 v[16:17], 0
	v_mov_b64_e32 v[18:19], 0
	v_mov_b64_e32 v[20:21], 0
	v_mov_b64_e32 v[22:23], 0
	v_mov_b64_e32 v[24:25], 0
	v_mov_b64_e32 v[26:27], 0
	v_mov_b64_e32 v[28:29], 0
	v_mov_b64_e32 v[30:31], 0
	v_mov_b64_e32 v[32:33], 0
	v_mov_b64_e32 v[34:35], 0
	v_mov_b64_e32 v[36:37], 0
	v_mov_b64_e32 v[38:39], 0
	v_mov_b64_e32 v[40:41], 0
	v_mov_b64_e32 v[42:43], 0
	v_mov_b64_e32 v[44:45], 0
	v_mov_b64_e32 v[46:47], 0
	v_mov_b64_e32 v[48:49], 0
	v_mov_b64_e32 v[50:51], 0
	v_mov_b64_e32 v[52:53], 0
	v_mov_b64_e32 v[54:55], 0
	v_mov_b64_e32 v[56:57], 0
	v_mov_b64_e32 v[58:59], 0
	v_mov_b64_e32 v[60:61], 0
	v_mov_b64_e32 v[62:63], 0
	v_mov_b64_e32 v[64:65], 0
	v_mov_b64_e32 v[66:67], 0
	v_mov_b64_e32 v[68:69], 0
	v_mov_b64_e32 v[70:71], 0
	v_mov_b64_e32 v[72:73], 0
	v_mov_b64_e32 v[74:75], 0
	v_mov_b64_e32 v[76:77], 0
	v_mov_b64_e32 v[78:79], 0
	v_mov_b64_e32 v[82:83], 0
	v_mov_b64_e32 v[84:85], 0
	v_mov_b64_e32 v[86:87], 0
	v_mov_b64_e32 v[88:89], 0
	v_mov_b64_e32 v[90:91], 0
	v_mov_b64_e32 v[92:93], 0
	v_mov_b64_e32 v[94:95], 0
	v_mov_b64_e32 v[96:97], 0
	v_mov_b64_e32 v[98:99], 0
	v_mov_b64_e32 v[100:101], 0
	v_mov_b64_e32 v[102:103], 0
	v_mov_b64_e32 v[104:105], 0
	v_mov_b64_e32 v[106:107], 0
	v_mov_b64_e32 v[108:109], 0
	v_mov_b64_e32 v[110:111], 0
	v_mov_b64_e32 v[112:113], 0
	v_mov_b64_e32 v[114:115], 0
	v_mov_b64_e32 v[116:117], 0
	v_mov_b64_e32 v[118:119], 0
	v_mov_b64_e32 v[120:121], 0
	v_mov_b64_e32 v[122:123], 0
	v_mov_b64_e32 v[124:125], 0
	v_mov_b64_e32 v[126:127], 0
	v_mov_b64_e32 v[128:129], 0
	v_readfirstlane_b32 s0, v167
	s_nop 3
	s_cmpk_gt_u32 s0, 0xff
	s_cbranch_scc1 .Lprio_k3
	s_setprio 1

; template <class Epi, bool ALIGN_EPI>
; __device__ __forceinline__ void gemm_phase(LAS unsigned char* lds, const Gemm g, const StaticOrder S, const Epi E) {
;     ...
;         const bool has_next = S.next(ui + 1, nxt);
;         const char* nA = has_next ? (const char*)g.A + (size_t)nxt.pm * tstepA + PG8_KOFS(nxt) : cA; const char* nB = has_next ? (const char*)g.Bt + (size_t)nxt.pn * tstepB + PG8_KOFS(nxt) : cB;
;     ...
;         for (int a = 0; a < 2; ++a)
; #pragma unroll
;             for (int b = 0; b < 2; ++b)
; #pragma unroll
;                 for (int m = 0; m < 4; ++m)
; #pragma unroll
;                     for (int n = 0; n < 2; ++n) acc[a][b][m][n] = (f32x4){0.f, 0.f, 0.f, 0.f};
.LBB0_1554:
	s_ashr_i32 s51, s50, 31
	s_lshl_b64 s[0:1], s[50:51], 19
	s_add_u32 s54, s94, s0
	s_addc_u32 s55, s95, s1
	s_and_b64 s[0:1], s[40:41], exec
	s_cselect_b32 s34, s55, s65
	s_cselect_b32 s35, s54, s64
	s_ashr_i32 s49, s48, 31
	s_lshl_b64 s[0:1], s[48:49], 19
	v_readlane_b32 s2, v255, 31
	s_add_u32 s62, s2, s0
	v_readlane_b32 s0, v255, 32
	s_addc_u32 s63, s0, s1
	s_and_b64 s[0:1], s[40:41], exec
	s_cselect_b32 s49, s63, s43
	s_cselect_b32 s51, s62, s42
	s_add_u32 s2, s64, 0x40080
	s_addc_u32 s3, s65, 0
	s_add_u32 s66, s42, 0x100
	v_mov_b32_e32 v0, 0
	s_addc_u32 s67, s43, 0
	s_mov_b32 s68, -2
	v_mov_b32_e32 v1, 0
	v_mov_b64_e32 v[2:3], 0
	v_mov_b64_e32 v[4:5], 0
	v_mov_b64_e32 v[6:7], 0
	v_mov_b64_e32 v[8:9], 0
	v_mov_b64_e32 v[10:11], 0
	v_mov_b64_e32 v[12:13], 0
	v_mov_b64_e32 v[14:15], 0
	v_mov_b64_e32 v[16:17], 0
	v_mov_b64_e32 v[18:19], 0
	v_mov_b64_e32 v[20:21], 0
	v_mov_b64_e32 v[22:23], 0
	v_mov_b64_e32 v[24:25], 0
	v_mov_b64_e32 v[26:27], 0
	v_mov_b64_e32 v[28:29], 0
	v_mov_b64_e32 v[30:31], 0
	v_mov_b64_e32 v[32:33], 0
	v_mov_b64_e32 v[34:35], 0
	v_mov_b64_e32 v[36:37], 0
	v_mov_b64_e32 v[38:39], 0
	v_mov_b64_e32 v[40:41], 0
	v_mov_b64_e32 v[42:43], 0
	v_mov_b64_e32 v[44:45], 0
	v_mov_b64_e32 v[46:47], 0
	v_mov_b64_e32 v[48:49], 0
	v_mov_b64_e32 v[50:51], 0
	v_mov_b64_e32 v[52:53], 0
	v_mov_b64_e32 v[54:55], 0
	v_mov_b64_e32 v[56:57], 0
	v_mov_b64_e32 v[58:59], 0
	v_mov_b64_e32 v[60:61], 0
	v_mov_b64_e32 v[62:63], 0
	v_mov_b64_e32 v[64:65], 0
	v_mov_b64_e32 v[66:67], 0
	v_mov_b64_e32 v[68:69], 0
	v_mov_b64_e32 v[70:71], 0
	v_mov_b64_e32 v[72:73], 0
	v_mov_b64_e32 v[74:75], 0
	v_mov_b64_e32 v[76:77], 0
	v_mov_b64_e32 v[78:79], 0
	v_mov_b64_e32 v[82:83], 0
	v_mov_b64_e32 v[84:85], 0
	v_mov_b64_e32 v[86:87], 0
	v_mov_b64_e32 v[88:89], 0
	v_mov_b64_e32 v[90:91], 0
	v_mov_b64_e32 v[92:93], 0
	v_mov_b64_e32 v[94:95], 0
	v_mov_b64_e32 v[96:97], 0
	v_mov_b64_e32 v[98:99], 0
	v_mov_b64_e32 v[100:101], 0
	v_mov_b64_e32 v[102:103], 0
	v_mov_b64_e32 v[104:105], 0
	v_mov_b64_e32 v[106:107], 0
	v_mov_b64_e32 v[108:109], 0
	v_mov_b64_e32 v[110:111], 0
	v_mov_b64_e32 v[112:113], 0
	v_mov_b64_e32 v[114:115], 0
	v_mov_b64_e32 v[116:117], 0
	v_mov_b64_e32 v[118:119], 0
	v_mov_b64_e32 v[120:121], 0
	v_mov_b64_e32 v[122:123], 0
	v_mov_b64_e32 v[124:125], 0
	v_mov_b64_e32 v[126:127], 0
	v_mov_b64_e32 v[128:129], 0
	v_readfirstlane_b32 s0, v167
	s_nop 3
	s_cmpk_gt_u32 s0, 0xff
	s_cbranch_scc1 .Lprio_k4
	s_setprio 1

; template <class Epi, bool ALIGN_EPI>
; __device__ __forceinline__ void gemm_phase(LAS unsigned char* lds, const Gemm g, const StaticOrder S, const Epi E) {
;     ...
;         for (int t = 0; t < nt; t += 2) {
;     ...
;         for (int a = 0; a < 2; ++a)
; #pragma unroll
;             for (int b = 0; b < 2; ++b)
; #pragma unroll
;                 for (int m = 0; m < 4; ++m)
; #pragma unroll
;                     for (int n = 0; n < 2; ++n) acc[a][b][m][n] = (f32x4){0.f, 0.f, 0.f, 0.f};
.LBB0_1756:
	s_add_u32 s26, s50, 0x100
	v_mov_b32_e32 v0, 0
	s_addc_u32 s27, s51, 0
	s_mov_b32 s28, -2
	v_mov_b32_e32 v1, 0
	v_mov_b64_e32 v[2:3], 0
	v_mov_b64_e32 v[4:5], 0
	v_mov_b64_e32 v[6:7], 0
	v_mov_b64_e32 v[8:9], 0
	v_mov_b64_e32 v[10:11], 0
	v_mov_b64_e32 v[12:13], 0
	v_mov_b64_e32 v[14:15], 0
	v_mov_b64_e32 v[16:17], 0
	v_mov_b64_e32 v[18:19], 0
	v_mov_b64_e32 v[20:21], 0
	v_mov_b64_e32 v[22:23], 0
	v_mov_b64_e32 v[24:25], 0
	v_mov_b64_e32 v[26:27], 0
	v_mov_b64_e32 v[28:29], 0
	v_mov_b64_e32 v[30:31], 0
	v_mov_b64_e32 v[32:33], 0
	v_mov_b64_e32 v[34:35], 0
	v_mov_b64_e32 v[36:37], 0
	v_mov_b64_e32 v[38:39], 0
	v_mov_b64_e32 v[40:41], 0
	v_mov_b64_e32 v[42:43], 0
	v_mov_b64_e32 v[44:45], 0
	v_mov_b64_e32 v[46:47], 0
	v_mov_b64_e32 v[48:49], 0
	v_mov_b64_e32 v[50:51], 0
	v_mov_b64_e32 v[52:53], 0
	v_mov_b64_e32 v[54:55], 0
	v_mov_b64_e32 v[56:57], 0
	v_mov_b64_e32 v[58:59], 0
	v_mov_b64_e32 v[60:61], 0
	v_mov_b64_e32 v[62:63], 0
	v_mov_b64_e32 v[64:65], 0
	v_mov_b64_e32 v[66:67], 0
	v_mov_b64_e32 v[68:69], 0
	v_mov_b64_e32 v[70:71], 0
	v_mov_b64_e32 v[72:73], 0
	v_mov_b64_e32 v[74:75], 0
	v_mov_b64_e32 v[76:77], 0
	v_mov_b64_e32 v[78:79], 0
	v_mov_b64_e32 v[82:83], 0
	v_mov_b64_e32 v[84:85], 0
	v_mov_b64_e32 v[86:87], 0
	v_mov_b64_e32 v[88:89], 0
	v_mov_b64_e32 v[90:91], 0
	v_mov_b64_e32 v[92:93], 0
	v_mov_b64_e32 v[94:95], 0
	v_mov_b64_e32 v[96:97], 0
	v_mov_b64_e32 v[98:99], 0
	v_mov_b64_e32 v[100:101], 0
	v_mov_b64_e32 v[102:103], 0
	v_mov_b64_e32 v[104:105], 0
	v_mov_b64_e32 v[106:107], 0
	v_mov_b64_e32 v[108:109], 0
	v_mov_b64_e32 v[110:111], 0
	v_mov_b64_e32 v[112:113], 0
	v_mov_b64_e32 v[114:115], 0
	v_mov_b64_e32 v[116:117], 0
	v_mov_b64_e32 v[118:119], 0
	v_mov_b64_e32 v[120:121], 0
	v_mov_b64_e32 v[122:123], 0
	v_mov_b64_e32 v[124:125], 0
	v_mov_b64_e32 v[126:127], 0
	v_mov_b64_e32 v[128:129], 0
	v_readfirstlane_b32 s0, v167
	s_nop 3
	s_cmpk_gt_u32 s0, 0xff
	s_cbranch_scc1 .Lprio_k5
	s_setprio 1

; template <class Epi, bool ALIGN_EPI>
; __device__ __forceinline__ void gemm_phase(LAS unsigned char* lds, const Gemm g, const StaticOrder S, const Epi E) {
;     ...
;         const bool has_next = S.next(ui + 1, nxt);
;         const char* nA = has_next ? (const char*)g.A + (size_t)nxt.pm * tstepA + PG8_KOFS(nxt) : cA; const char* nB = has_next ? (const char*)g.Bt + (size_t)nxt.pn * tstepB + PG8_KOFS(nxt) : cB;
;     ...
;         for (int a = 0; a < 2; ++a)
; #pragma unroll
;             for (int b = 0; b < 2; ++b)
; #pragma unroll
;                 for (int m = 0; m < 4; ++m)
; #pragma unroll
;                     for (int n = 0; n < 2; ++n) acc[a][b][m][n] = (f32x4){0.f, 0.f, 0.f, 0.f};
.LBB0_1814:
	s_ashr_i32 s47, s46, 31
	s_lshl_b64 s[0:1], s[46:47], 17
	v_readlane_b32 s12, v255, 37
	s_add_u32 s50, s12, s0
	v_readlane_b32 s0, v255, 38
	s_addc_u32 s51, s0, s1
	s_and_b64 s[0:1], s[42:43], exec
	v_mov_b32_e32 v0, 0
	s_cselect_b32 s47, s51, s53
	s_cselect_b32 s93, s50, s52
	s_mov_b64 s[64:65], 0
	s_mov_b64 s[42:43], -1
	s_mov_b64 s[62:63], 0
	v_mov_b32_e32 v1, 0
	v_mov_b64_e32 v[2:3], 0
	v_mov_b64_e32 v[4:5], 0
	v_mov_b64_e32 v[6:7], 0
	v_mov_b64_e32 v[8:9], 0
	v_mov_b64_e32 v[10:11], 0
	v_mov_b64_e32 v[12:13], 0
	v_mov_b64_e32 v[14:15], 0
	v_mov_b64_e32 v[16:17], 0
	v_mov_b64_e32 v[18:19], 0
	v_mov_b64_e32 v[20:21], 0
	v_mov_b64_e32 v[22:23], 0
	v_mov_b64_e32 v[24:25], 0
	v_mov_b64_e32 v[26:27], 0
	v_mov_b64_e32 v[28:29], 0
	v_mov_b64_e32 v[30:31], 0
	v_mov_b64_e32 v[32:33], 0
	v_mov_b64_e32 v[34:35], 0
	v_mov_b64_e32 v[36:37], 0
	v_mov_b64_e32 v[38:39], 0
	v_mov_b64_e32 v[40:41], 0
	v_mov_b64_e32 v[42:43], 0
	v_mov_b64_e32 v[44:45], 0
	v_mov_b64_e32 v[46:47], 0
	v_mov_b64_e32 v[48:49], 0
	v_mov_b64_e32 v[50:51], 0
	v_mov_b64_e32 v[52:53], 0
	v_mov_b64_e32 v[54:55], 0
	v_mov_b64_e32 v[56:57], 0
	v_mov_b64_e32 v[58:59], 0
	v_mov_b64_e32 v[60:61], 0
	v_mov_b64_e32 v[62:63], 0
	v_mov_b64_e32 v[64:65], 0
	v_mov_b64_e32 v[66:67], 0
	v_mov_b64_e32 v[68:69], 0
	v_mov_b64_e32 v[70:71], 0
	v_mov_b64_e32 v[72:73], 0
	v_mov_b64_e32 v[74:75], 0
	v_mov_b64_e32 v[76:77], 0
	v_mov_b64_e32 v[78:79], 0
	v_mov_b64_e32 v[82:83], 0
	v_mov_b64_e32 v[84:85], 0
	v_mov_b64_e32 v[86:87], 0
	v_mov_b64_e32 v[88:89], 0
	v_mov_b64_e32 v[90:91], 0
	v_mov_b64_e32 v[92:93], 0
	v_mov_b64_e32 v[94:95], 0
	v_mov_b64_e32 v[96:97], 0
	v_mov_b64_e32 v[98:99], 0
	v_mov_b64_e32 v[100:101], 0
	v_mov_b64_e32 v[102:103], 0
	v_mov_b64_e32 v[104:105], 0
	v_mov_b64_e32 v[106:107], 0
	v_mov_b64_e32 v[108:109], 0
	v_mov_b64_e32 v[110:111], 0
	v_mov_b64_e32 v[112:113], 0
	v_mov_b64_e32 v[114:115], 0
	v_mov_b64_e32 v[116:117], 0
	v_mov_b64_e32 v[118:119], 0
	v_mov_b64_e32 v[120:121], 0
	v_mov_b64_e32 v[122:123], 0
	v_mov_b64_e32 v[124:125], 0
	v_mov_b64_e32 v[126:127], 0
	v_mov_b64_e32 v[128:129], 0
	v_readfirstlane_b32 s0, v167
	s_nop 3
	s_cmpk_gt_u32 s0, 0xff
	s_cbranch_scc1 .Lprio_k6
	s_setprio 1

; template <class Epi, bool ALIGN_EPI>
; __device__ __forceinline__ void gemm_phase(LAS unsigned char* lds, const Gemm g, const StaticOrder S, const Epi E) {
;     ...
;         const bool has_next = S.next(ui + 1, nxt);
;         const char* nA = has_next ? (const char*)g.A + (size_t)nxt.pm * tstepA + PG8_KOFS(nxt) : cA; const char* nB = has_next ? (const char*)g.Bt + (size_t)nxt.pn * tstepB + PG8_KOFS(nxt) : cB;
;     ...
;         for (int a = 0; a < 2; ++a)
; #pragma unroll
;             for (int b = 0; b < 2; ++b)
; #pragma unroll
;                 for (int m = 0; m < 4; ++m)
; #pragma unroll
;                     for (int n = 0; n < 2; ++n) acc[a][b][m][n] = (f32x4){0.f, 0.f, 0.f, 0.f};
.LBB0_2014:
	s_ashr_i32 s47, s46, 31
	s_lshl_b64 s[0:1], s[46:47], 19
	v_readlane_b32 s12, v255, 39
	s_add_u32 s50, s12, s0
	v_readlane_b32 s0, v255, 40
	s_addc_u32 s51, s0, s1
	s_and_b64 s[0:1], s[42:43], exec
	s_cselect_b32 s34, s51, s63
	s_cselect_b32 s35, s50, s62
	s_add_u32 s47, s62, 0x100
	v_mov_b32_e32 v0, 0
	s_addc_u32 s53, s63, 0
	s_mov_b32 s71, -2
	v_mov_b32_e32 v1, 0
	v_mov_b64_e32 v[2:3], 0
	v_mov_b64_e32 v[4:5], 0
	v_mov_b64_e32 v[6:7], 0
	v_mov_b64_e32 v[8:9], 0
	v_mov_b64_e32 v[10:11], 0
	v_mov_b64_e32 v[12:13], 0
	v_mov_b64_e32 v[14:15], 0
	v_mov_b64_e32 v[16:17], 0
	v_mov_b64_e32 v[18:19], 0
	v_mov_b64_e32 v[20:21], 0
	v_mov_b64_e32 v[22:23], 0
	v_mov_b64_e32 v[24:25], 0
	v_mov_b64_e32 v[26:27], 0
	v_mov_b64_e32 v[28:29], 0
	v_mov_b64_e32 v[30:31], 0
	v_mov_b64_e32 v[32:33], 0
	v_mov_b64_e32 v[34:35], 0
	v_mov_b64_e32 v[36:37], 0
	v_mov_b64_e32 v[38:39], 0
	v_mov_b64_e32 v[40:41], 0
	v_mov_b64_e32 v[42:43], 0
	v_mov_b64_e32 v[44:45], 0
	v_mov_b64_e32 v[46:47], 0
	v_mov_b64_e32 v[48:49], 0
	v_mov_b64_e32 v[50:51], 0
	v_mov_b64_e32 v[52:53], 0
	v_mov_b64_e32 v[54:55], 0
	v_mov_b64_e32 v[56:57], 0
	v_mov_b64_e32 v[58:59], 0
	v_mov_b64_e32 v[60:61], 0
	v_mov_b64_e32 v[62:63], 0
	v_mov_b64_e32 v[64:65], 0
	v_mov_b64_e32 v[66:67], 0
	v_mov_b64_e32 v[68:69], 0
	v_mov_b64_e32 v[70:71], 0
	v_mov_b64_e32 v[72:73], 0
	v_mov_b64_e32 v[74:75], 0
	v_mov_b64_e32 v[76:77], 0
	v_mov_b64_e32 v[78:79], 0
	v_mov_b64_e32 v[82:83], 0
	v_mov_b64_e32 v[84:85], 0
	v_mov_b64_e32 v[86:87], 0
	v_mov_b64_e32 v[88:89], 0
	v_mov_b64_e32 v[90:91], 0
	v_mov_b64_e32 v[92:93], 0
	v_mov_b64_e32 v[94:95], 0
	v_mov_b64_e32 v[96:97], 0
	v_mov_b64_e32 v[98:99], 0
	v_mov_b64_e32 v[100:101], 0
	v_mov_b64_e32 v[102:103], 0
	v_mov_b64_e32 v[104:105], 0
	v_mov_b64_e32 v[106:107], 0
	v_mov_b64_e32 v[108:109], 0
	v_mov_b64_e32 v[110:111], 0
	v_mov_b64_e32 v[112:113], 0
	v_mov_b64_e32 v[114:115], 0
	v_mov_b64_e32 v[116:117], 0
	v_mov_b64_e32 v[118:119], 0
	v_mov_b64_e32 v[120:121], 0
	v_mov_b64_e32 v[122:123], 0
	v_mov_b64_e32 v[124:125], 0
	v_mov_b64_e32 v[126:127], 0
	v_mov_b64_e32 v[128:129], 0
	v_readfirstlane_b32 s0, v167
	s_nop 3
	s_cmpk_gt_u32 s0, 0xff
	s_cbranch_scc1 .Lprio_k7
	s_setprio 1
